# K loops: scalar pointer-selection chain issued after the phase-1 reads and stage loads instead of between the ds_reads
# speedup vs baseline: 1.0015x; 1.0015x over previous
.LBB0_236:
	ds_read_b128 v[144:147], v160
	ds_read_b128 v[148:151], v161
	ds_read_b128 v[178:181], v163
	ds_read_b128 v[182:185], v164
	s_mov_b32 m0, s61
	ds_read_b128 v[186:189], v158
	ds_read_b128 v[190:193], v158 offset:1024
	ds_read_b128 v[194:197], v158 offset:2048
	ds_read_b128 v[198:201], v158 offset:3072
	ds_read_b128 v[202:205], v158 offset:4096
	ds_read_b128 v[206:209], v158 offset:5120
	ds_read_b128 v[210:213], v158 offset:6144
	ds_read_b128 v[214:217], v158 offset:7168
	global_load_lds_dwordx4 v136, s[6:7]
	s_mov_b32 m0, s64
	s_nop 0
	global_load_lds_dwordx4 v138, s[6:7]
	s_add_i32 s14, s2, 2
	s_add_u32 s8, s6, 0x80
	s_addc_u32 s3, s7, 0
	s_cmp_eq_u32 s56, s2
	s_cselect_b32 s2, s62, s8
	s_cselect_b32 s3, s63, s3
	s_cselect_b32 s9, s1, s11
	s_cselect_b32 s8, s0, s10
	s_waitcnt lgkmcnt(8)
	s_barrier
	s_waitcnt lgkmcnt(0)
	s_waitcnt lgkmcnt(0)
	v_mfma_f32_16x16x32_bf16 v[126:129], v[144:147], v[186:189], v[126:129]
	v_mfma_f32_16x16x32_bf16 v[122:125], v[178:181], v[186:189], v[122:125]
	v_mfma_f32_16x16x32_bf16 v[110:113], v[144:147], v[194:197], v[110:113]
	v_mfma_f32_16x16x32_bf16 v[106:109], v[178:181], v[194:197], v[106:109]
	v_mfma_f32_16x16x32_bf16 v[94:97], v[144:147], v[202:205], v[94:97]
	v_mfma_f32_16x16x32_bf16 v[90:93], v[178:181], v[202:205], v[90:93]
	v_mfma_f32_16x16x32_bf16 v[78:81], v[144:147], v[210:213], v[78:81]
	v_mfma_f32_16x16x32_bf16 v[74:77], v[178:181], v[210:213], v[74:77]
	v_mfma_f32_16x16x32_bf16 v[126:129], v[148:151], v[190:193], v[126:129]
	v_mfma_f32_16x16x32_bf16 v[122:125], v[182:185], v[190:193], v[122:125]
	v_mfma_f32_16x16x32_bf16 v[110:113], v[148:151], v[198:201], v[110:113]
	v_mfma_f32_16x16x32_bf16 v[106:109], v[182:185], v[198:201], v[106:109]
	v_mfma_f32_16x16x32_bf16 v[94:97], v[148:151], v[206:209], v[94:97]
	v_mfma_f32_16x16x32_bf16 v[90:93], v[182:185], v[206:209], v[90:93]
	v_mfma_f32_16x16x32_bf16 v[78:81], v[148:151], v[214:217], v[78:81]
	v_mfma_f32_16x16x32_bf16 v[74:77], v[182:185], v[214:217], v[74:77]
	s_barrier
	s_mov_b32 m0, s30
	ds_read_b128 v[218:221], v165
	ds_read_b128 v[222:225], v166
	ds_read_b128 v[226:229], v167
	ds_read_b128 v[230:233], v168
	global_load_lds_dwordx4 v130, s[8:9]
	s_mov_b32 m0, s31
	s_nop 0
	global_load_lds_dwordx4 v132, s[8:9]
	s_barrier
	s_waitcnt lgkmcnt(0)
	s_waitcnt lgkmcnt(0)
	v_mfma_f32_16x16x32_bf16 v[118:121], v[218:221], v[186:189], v[118:121]
	v_mfma_f32_16x16x32_bf16 v[114:117], v[226:229], v[186:189], v[114:117]
	v_mfma_f32_16x16x32_bf16 v[102:105], v[218:221], v[194:197], v[102:105]
	v_mfma_f32_16x16x32_bf16 v[98:101], v[226:229], v[194:197], v[98:101]
	v_mfma_f32_16x16x32_bf16 v[86:89], v[218:221], v[202:205], v[86:89]
	v_mfma_f32_16x16x32_bf16 v[82:85], v[226:229], v[202:205], v[82:85]
	v_mfma_f32_16x16x32_bf16 v[70:73], v[218:221], v[210:213], v[70:73]
	v_mfma_f32_16x16x32_bf16 v[66:69], v[226:229], v[210:213], v[66:69]
	v_mfma_f32_16x16x32_bf16 v[118:121], v[222:225], v[190:193], v[118:121]
	v_mfma_f32_16x16x32_bf16 v[114:117], v[230:233], v[190:193], v[114:117]
	v_mfma_f32_16x16x32_bf16 v[102:105], v[222:225], v[198:201], v[102:105]
	v_mfma_f32_16x16x32_bf16 v[98:101], v[230:233], v[198:201], v[98:101]
	v_mfma_f32_16x16x32_bf16 v[86:89], v[222:225], v[206:209], v[86:89]
	v_mfma_f32_16x16x32_bf16 v[82:85], v[230:233], v[206:209], v[82:85]
	v_mfma_f32_16x16x32_bf16 v[70:73], v[222:225], v[214:217], v[70:73]
	v_mfma_f32_16x16x32_bf16 v[66:69], v[230:233], v[214:217], v[66:69]
	s_mov_b32 m0, s29
	s_barrier
	ds_read_b128 v[186:189], v158 offset:16384
	ds_read_b128 v[190:193], v158 offset:17408
	ds_read_b128 v[194:197], v158 offset:18432
	ds_read_b128 v[198:201], v158 offset:19456
	ds_read_b128 v[202:205], v158 offset:20480
	ds_read_b128 v[206:209], v158 offset:21504
	ds_read_b128 v[210:213], v158 offset:22528
	ds_read_b128 v[214:217], v158 offset:23552
	global_load_lds_dwordx4 v130, s[2:3]
	s_mov_b32 m0, s33
	s_nop 0
	global_load_lds_dwordx4 v132, s[2:3]
	s_barrier
	s_waitcnt lgkmcnt(0)
	s_waitcnt lgkmcnt(0)
	v_mfma_f32_16x16x32_bf16 v[62:65], v[144:147], v[186:189], v[62:65]
	v_mfma_f32_16x16x32_bf16 v[58:61], v[178:181], v[186:189], v[58:61]
	v_mfma_f32_16x16x32_bf16 v[46:49], v[144:147], v[194:197], v[46:49]
	v_mfma_f32_16x16x32_bf16 v[42:45], v[178:181], v[194:197], v[42:45]
	v_mfma_f32_16x16x32_bf16 v[30:33], v[144:147], v[202:205], v[30:33]
	v_mfma_f32_16x16x32_bf16 v[26:29], v[178:181], v[202:205], v[26:29]
	v_mfma_f32_16x16x32_bf16 v[14:17], v[144:147], v[210:213], v[14:17]
	v_mfma_f32_16x16x32_bf16 v[10:13], v[178:181], v[210:213], v[10:13]
	v_mfma_f32_16x16x32_bf16 v[62:65], v[148:151], v[190:193], v[62:65]
	v_mfma_f32_16x16x32_bf16 v[58:61], v[182:185], v[190:193], v[58:61]
	v_mfma_f32_16x16x32_bf16 v[46:49], v[148:151], v[198:201], v[46:49]
	v_mfma_f32_16x16x32_bf16 v[42:45], v[182:185], v[198:201], v[42:45]
	v_mfma_f32_16x16x32_bf16 v[30:33], v[148:151], v[206:209], v[30:33]
	v_mfma_f32_16x16x32_bf16 v[26:29], v[182:185], v[206:209], v[26:29]
	v_mfma_f32_16x16x32_bf16 v[14:17], v[148:151], v[214:217], v[14:17]
	v_mfma_f32_16x16x32_bf16 v[10:13], v[182:185], v[214:217], v[10:13]
	s_barrier
	s_mov_b32 m0, s34
	s_nop 0
	global_load_lds_dwordx4 v243, s[8:9]
	s_mov_b32 m0, s35
	s_nop 0
	global_load_lds_dwordx4 v242, s[8:9]
	s_waitcnt vmcnt(6)
	s_barrier
	v_mfma_f32_16x16x32_bf16 v[54:57], v[218:221], v[186:189], v[54:57]
	v_mfma_f32_16x16x32_bf16 v[50:53], v[226:229], v[186:189], v[50:53]
	v_mfma_f32_16x16x32_bf16 v[38:41], v[218:221], v[194:197], v[38:41]
	v_mfma_f32_16x16x32_bf16 v[34:37], v[226:229], v[194:197], v[34:37]
	v_mfma_f32_16x16x32_bf16 v[22:25], v[218:221], v[202:205], v[22:25]
	v_mfma_f32_16x16x32_bf16 v[18:21], v[226:229], v[202:205], v[18:21]
	v_mfma_f32_16x16x32_bf16 v[6:9], v[218:221], v[210:213], v[6:9]
	v_mfma_f32_16x16x32_bf16 v[2:5], v[226:229], v[210:213], v[2:5]
	v_mfma_f32_16x16x32_bf16 v[54:57], v[222:225], v[190:193], v[54:57]
	v_mfma_f32_16x16x32_bf16 v[50:53], v[230:233], v[190:193], v[50:53]
	v_mfma_f32_16x16x32_bf16 v[38:41], v[222:225], v[198:201], v[38:41]
	v_mfma_f32_16x16x32_bf16 v[34:37], v[230:233], v[198:201], v[34:37]
	v_mfma_f32_16x16x32_bf16 v[22:25], v[222:225], v[206:209], v[22:25]
	v_mfma_f32_16x16x32_bf16 v[18:21], v[230:233], v[206:209], v[18:21]
	v_mfma_f32_16x16x32_bf16 v[6:9], v[222:225], v[214:217], v[6:9]
	v_mfma_f32_16x16x32_bf16 v[2:5], v[230:233], v[214:217], v[2:5]
	s_barrier
	ds_read_b128 v[144:147], v169
	ds_read_b128 v[148:151], v170
	ds_read_b128 v[178:181], v171
	ds_read_b128 v[182:185], v172
	s_mov_b32 m0, s38
	ds_read_b128 v[186:189], v158 offset:32768
	ds_read_b128 v[190:193], v158 offset:33792
	ds_read_b128 v[194:197], v158 offset:34816
	ds_read_b128 v[198:201], v158 offset:35840
	ds_read_b128 v[202:205], v158 offset:36864
	ds_read_b128 v[206:209], v158 offset:37888
	ds_read_b128 v[210:213], v158 offset:38912
	ds_read_b128 v[214:217], v158 offset:39936
	global_load_lds_dwordx4 v243, s[2:3]
	s_mov_b32 m0, s39
	s_nop 0
	global_load_lds_dwordx4 v242, s[2:3]
	s_waitcnt lgkmcnt(8)
	s_barrier
	s_waitcnt lgkmcnt(0)
	s_waitcnt lgkmcnt(0)
	v_mfma_f32_16x16x32_bf16 v[126:129], v[144:147], v[186:189], v[126:129]
	v_mfma_f32_16x16x32_bf16 v[122:125], v[178:181], v[186:189], v[122:125]
	v_mfma_f32_16x16x32_bf16 v[110:113], v[144:147], v[194:197], v[110:113]
	v_mfma_f32_16x16x32_bf16 v[106:109], v[178:181], v[194:197], v[106:109]
	v_mfma_f32_16x16x32_bf16 v[94:97], v[144:147], v[202:205], v[94:97]
	v_mfma_f32_16x16x32_bf16 v[90:93], v[178:181], v[202:205], v[90:93]
	v_mfma_f32_16x16x32_bf16 v[78:81], v[144:147], v[210:213], v[78:81]
	v_mfma_f32_16x16x32_bf16 v[74:77], v[178:181], v[210:213], v[74:77]
	v_mfma_f32_16x16x32_bf16 v[126:129], v[148:151], v[190:193], v[126:129]
	v_mfma_f32_16x16x32_bf16 v[122:125], v[182:185], v[190:193], v[122:125]
	v_mfma_f32_16x16x32_bf16 v[110:113], v[148:151], v[198:201], v[110:113]
	v_mfma_f32_16x16x32_bf16 v[106:109], v[182:185], v[198:201], v[106:109]
	v_mfma_f32_16x16x32_bf16 v[94:97], v[148:151], v[206:209], v[94:97]
	v_mfma_f32_16x16x32_bf16 v[90:93], v[182:185], v[206:209], v[90:93]
	v_mfma_f32_16x16x32_bf16 v[78:81], v[148:151], v[214:217], v[78:81]
	v_mfma_f32_16x16x32_bf16 v[74:77], v[182:185], v[214:217], v[74:77]
	s_barrier
	s_sub_u32 m0, s41, 0x80
	ds_read_b128 v[218:221], v173
	ds_read_b128 v[222:225], v174
	ds_read_b128 v[226:229], v175
	ds_read_b128 v[230:233], v176
	global_load_lds_dwordx4 v130, s[8:9] offset:128
	s_sub_u32 m0, s42, 0x80
	s_nop 0
	global_load_lds_dwordx4 v132, s[8:9] offset:128
	s_barrier
	s_waitcnt lgkmcnt(0)
	s_waitcnt lgkmcnt(0)
	v_mfma_f32_16x16x32_bf16 v[118:121], v[218:221], v[186:189], v[118:121]
	v_mfma_f32_16x16x32_bf16 v[114:117], v[226:229], v[186:189], v[114:117]
	v_mfma_f32_16x16x32_bf16 v[102:105], v[218:221], v[194:197], v[102:105]
	v_mfma_f32_16x16x32_bf16 v[98:101], v[226:229], v[194:197], v[98:101]
	v_mfma_f32_16x16x32_bf16 v[86:89], v[218:221], v[202:205], v[86:89]
	v_mfma_f32_16x16x32_bf16 v[82:85], v[226:229], v[202:205], v[82:85]
	v_mfma_f32_16x16x32_bf16 v[70:73], v[218:221], v[210:213], v[70:73]
	v_mfma_f32_16x16x32_bf16 v[66:69], v[226:229], v[210:213], v[66:69]
	v_mfma_f32_16x16x32_bf16 v[118:121], v[222:225], v[190:193], v[118:121]
	v_mfma_f32_16x16x32_bf16 v[114:117], v[230:233], v[190:193], v[114:117]
	v_mfma_f32_16x16x32_bf16 v[102:105], v[222:225], v[198:201], v[102:105]
	v_mfma_f32_16x16x32_bf16 v[98:101], v[230:233], v[198:201], v[98:101]
	v_mfma_f32_16x16x32_bf16 v[86:89], v[222:225], v[206:209], v[86:89]
	v_mfma_f32_16x16x32_bf16 v[82:85], v[230:233], v[206:209], v[82:85]
	v_mfma_f32_16x16x32_bf16 v[70:73], v[222:225], v[214:217], v[70:73]
	v_mfma_f32_16x16x32_bf16 v[66:69], v[230:233], v[214:217], v[66:69]
	s_sub_u32 m0, s43, 0x80
	s_barrier
	ds_read_b128 v[186:189], v158 offset:49152
	ds_read_b128 v[190:193], v158 offset:50176
	ds_read_b128 v[194:197], v158 offset:51200
	ds_read_b128 v[198:201], v158 offset:52224
	ds_read_b128 v[202:205], v158 offset:53248
	ds_read_b128 v[206:209], v158 offset:54272
	ds_read_b128 v[210:213], v158 offset:55296
	ds_read_b128 v[214:217], v158 offset:56320
	global_load_lds_dwordx4 v130, s[2:3] offset:128
	s_sub_u32 m0, s48, 0x80
	s_nop 0
	global_load_lds_dwordx4 v132, s[2:3] offset:128
	s_barrier
	s_waitcnt lgkmcnt(0)
	s_waitcnt lgkmcnt(0)
	v_mfma_f32_16x16x32_bf16 v[62:65], v[144:147], v[186:189], v[62:65]
	v_mfma_f32_16x16x32_bf16 v[58:61], v[178:181], v[186:189], v[58:61]
	v_mfma_f32_16x16x32_bf16 v[46:49], v[144:147], v[194:197], v[46:49]
	v_mfma_f32_16x16x32_bf16 v[42:45], v[178:181], v[194:197], v[42:45]
	v_mfma_f32_16x16x32_bf16 v[30:33], v[144:147], v[202:205], v[30:33]
	v_mfma_f32_16x16x32_bf16 v[26:29], v[178:181], v[202:205], v[26:29]
	v_mfma_f32_16x16x32_bf16 v[14:17], v[144:147], v[210:213], v[14:17]
	v_mfma_f32_16x16x32_bf16 v[10:13], v[178:181], v[210:213], v[10:13]
	v_mfma_f32_16x16x32_bf16 v[62:65], v[148:151], v[190:193], v[62:65]
	v_mfma_f32_16x16x32_bf16 v[58:61], v[182:185], v[190:193], v[58:61]
	v_mfma_f32_16x16x32_bf16 v[46:49], v[148:151], v[198:201], v[46:49]
	v_mfma_f32_16x16x32_bf16 v[42:45], v[182:185], v[198:201], v[42:45]
	v_mfma_f32_16x16x32_bf16 v[30:33], v[148:151], v[206:209], v[30:33]
	v_mfma_f32_16x16x32_bf16 v[26:29], v[182:185], v[206:209], v[26:29]
	v_mfma_f32_16x16x32_bf16 v[14:17], v[148:151], v[214:217], v[14:17]
	v_mfma_f32_16x16x32_bf16 v[10:13], v[182:185], v[214:217], v[10:13]
	s_barrier
	s_sub_u32 m0, s49, 0x80
	s_nop 0
	global_load_lds_dwordx4 v243, s[8:9] offset:128
	s_sub_u32 m0, s50, 0x80
	s_nop 0
	global_load_lds_dwordx4 v242, s[8:9] offset:128
	s_waitcnt vmcnt(6)
	s_barrier
	v_mfma_f32_16x16x32_bf16 v[54:57], v[218:221], v[186:189], v[54:57]
	v_mfma_f32_16x16x32_bf16 v[50:53], v[226:229], v[186:189], v[50:53]
	v_mfma_f32_16x16x32_bf16 v[38:41], v[218:221], v[194:197], v[38:41]
	v_mfma_f32_16x16x32_bf16 v[34:37], v[226:229], v[194:197], v[34:37]
	v_mfma_f32_16x16x32_bf16 v[22:25], v[218:221], v[202:205], v[22:25]
	v_mfma_f32_16x16x32_bf16 v[18:21], v[226:229], v[202:205], v[18:21]
	v_mfma_f32_16x16x32_bf16 v[6:9], v[218:221], v[210:213], v[6:9]
	v_mfma_f32_16x16x32_bf16 v[2:5], v[226:229], v[210:213], v[2:5]
	v_mfma_f32_16x16x32_bf16 v[54:57], v[222:225], v[190:193], v[54:57]
	v_mfma_f32_16x16x32_bf16 v[50:53], v[230:233], v[190:193], v[50:53]
	v_mfma_f32_16x16x32_bf16 v[38:41], v[222:225], v[198:201], v[38:41]
	v_mfma_f32_16x16x32_bf16 v[34:37], v[230:233], v[198:201], v[34:37]
	v_mfma_f32_16x16x32_bf16 v[22:25], v[222:225], v[206:209], v[22:25]
	v_mfma_f32_16x16x32_bf16 v[18:21], v[230:233], v[206:209], v[18:21]
	v_mfma_f32_16x16x32_bf16 v[6:9], v[222:225], v[214:217], v[6:9]
	v_mfma_f32_16x16x32_bf16 v[2:5], v[230:233], v[214:217], v[2:5]
	s_add_u32 s6, s6, 0x100
	s_addc_u32 s7, s7, 0
	s_add_u32 s10, s10, 0x100
	s_addc_u32 s11, s11, 0
	s_cmp_ge_i32 s14, s51
	s_mov_b32 s2, s14
	s_barrier
	s_cbranch_scc0 .LBB0_236

.LBB0_997:
	ds_read_b128 v[142:145], v168
	ds_read_b128 v[146:149], v169
	ds_read_b128 v[150:153], v170
	ds_read_b128 v[154:157], v171
	s_mov_b32 m0, s51
	ds_read_b128 v[186:189], v166
	ds_read_b128 v[190:193], v166 offset:1024
	ds_read_b128 v[194:197], v166 offset:2048
	ds_read_b128 v[198:201], v166 offset:3072
	ds_read_b128 v[202:205], v166 offset:4096
	ds_read_b128 v[206:209], v166 offset:5120
	ds_read_b128 v[210:213], v166 offset:6144
	ds_read_b128 v[214:217], v166 offset:7168
	global_load_lds_dwordx4 v134, s[24:25]
	s_mov_b32 m0, s52
	s_nop 0
	global_load_lds_dwordx4 v136, s[24:25]
	s_add_i32 s57, s2, 2
	s_add_u32 s26, s24, 0x80
	s_addc_u32 s3, s25, 0
	s_cmp_eq_u32 s46, s2
	s_cselect_b32 s2, s10, s26
	s_cselect_b32 s3, s11, s3
	s_cselect_b32 s27, s1, s37
	s_cselect_b32 s26, s0, s36
	s_waitcnt lgkmcnt(8)
	s_barrier
	s_waitcnt lgkmcnt(0)
	s_waitcnt lgkmcnt(0)
	v_mfma_f32_16x16x32_bf16 v[126:129], v[142:145], v[186:189], v[126:129]
	v_mfma_f32_16x16x32_bf16 v[122:125], v[150:153], v[186:189], v[122:125]
	v_mfma_f32_16x16x32_bf16 v[110:113], v[142:145], v[194:197], v[110:113]
	v_mfma_f32_16x16x32_bf16 v[106:109], v[150:153], v[194:197], v[106:109]
	v_mfma_f32_16x16x32_bf16 v[94:97], v[142:145], v[202:205], v[94:97]
	v_mfma_f32_16x16x32_bf16 v[90:93], v[150:153], v[202:205], v[90:93]
	v_mfma_f32_16x16x32_bf16 v[78:81], v[142:145], v[210:213], v[78:81]
	v_mfma_f32_16x16x32_bf16 v[74:77], v[150:153], v[210:213], v[74:77]
	v_mfma_f32_16x16x32_bf16 v[126:129], v[146:149], v[190:193], v[126:129]
	v_mfma_f32_16x16x32_bf16 v[122:125], v[154:157], v[190:193], v[122:125]
	v_mfma_f32_16x16x32_bf16 v[110:113], v[146:149], v[198:201], v[110:113]
	v_mfma_f32_16x16x32_bf16 v[106:109], v[154:157], v[198:201], v[106:109]
	v_mfma_f32_16x16x32_bf16 v[94:97], v[146:149], v[206:209], v[94:97]
	v_mfma_f32_16x16x32_bf16 v[90:93], v[154:157], v[206:209], v[90:93]
	v_mfma_f32_16x16x32_bf16 v[78:81], v[146:149], v[214:217], v[78:81]
	v_mfma_f32_16x16x32_bf16 v[74:77], v[154:157], v[214:217], v[74:77]
	s_barrier
	s_mov_b32 m0, s29
	ds_read_b128 v[218:221], v172
	ds_read_b128 v[222:225], v173
	ds_read_b128 v[226:229], v174
	ds_read_b128 v[230:233], v175
	global_load_lds_dwordx4 v130, s[26:27]
	s_mov_b32 m0, s30
	s_nop 0
	global_load_lds_dwordx4 v132, s[26:27]
	s_barrier
	s_waitcnt lgkmcnt(0)
	s_waitcnt lgkmcnt(0)
	v_mfma_f32_16x16x32_bf16 v[118:121], v[218:221], v[186:189], v[118:121]
	v_mfma_f32_16x16x32_bf16 v[114:117], v[226:229], v[186:189], v[114:117]
	v_mfma_f32_16x16x32_bf16 v[102:105], v[218:221], v[194:197], v[102:105]
	v_mfma_f32_16x16x32_bf16 v[98:101], v[226:229], v[194:197], v[98:101]
	v_mfma_f32_16x16x32_bf16 v[86:89], v[218:221], v[202:205], v[86:89]
	v_mfma_f32_16x16x32_bf16 v[82:85], v[226:229], v[202:205], v[82:85]
	v_mfma_f32_16x16x32_bf16 v[70:73], v[218:221], v[210:213], v[70:73]
	v_mfma_f32_16x16x32_bf16 v[66:69], v[226:229], v[210:213], v[66:69]
	v_mfma_f32_16x16x32_bf16 v[118:121], v[222:225], v[190:193], v[118:121]
	v_mfma_f32_16x16x32_bf16 v[114:117], v[230:233], v[190:193], v[114:117]
	v_mfma_f32_16x16x32_bf16 v[102:105], v[222:225], v[198:201], v[102:105]
	v_mfma_f32_16x16x32_bf16 v[98:101], v[230:233], v[198:201], v[98:101]
	v_mfma_f32_16x16x32_bf16 v[86:89], v[222:225], v[206:209], v[86:89]
	v_mfma_f32_16x16x32_bf16 v[82:85], v[230:233], v[206:209], v[82:85]
	v_mfma_f32_16x16x32_bf16 v[70:73], v[222:225], v[214:217], v[70:73]
	v_mfma_f32_16x16x32_bf16 v[66:69], v[230:233], v[214:217], v[66:69]
	s_mov_b32 m0, s28
	s_barrier
	ds_read_b128 v[186:189], v166 offset:16384
	ds_read_b128 v[190:193], v166 offset:17408
	ds_read_b128 v[194:197], v166 offset:18432
	ds_read_b128 v[198:201], v166 offset:19456
	ds_read_b128 v[202:205], v166 offset:20480
	ds_read_b128 v[206:209], v166 offset:21504
	ds_read_b128 v[210:213], v166 offset:22528
	ds_read_b128 v[214:217], v166 offset:23552
	global_load_lds_dwordx4 v130, s[2:3]
	s_mov_b32 m0, s31
	s_nop 0
	global_load_lds_dwordx4 v132, s[2:3]
	s_barrier
	s_waitcnt lgkmcnt(0)
	s_waitcnt lgkmcnt(0)
	v_mfma_f32_16x16x32_bf16 v[62:65], v[142:145], v[186:189], v[62:65]
	v_mfma_f32_16x16x32_bf16 v[58:61], v[150:153], v[186:189], v[58:61]
	v_mfma_f32_16x16x32_bf16 v[46:49], v[142:145], v[194:197], v[46:49]
	v_mfma_f32_16x16x32_bf16 v[42:45], v[150:153], v[194:197], v[42:45]
	v_mfma_f32_16x16x32_bf16 v[30:33], v[142:145], v[202:205], v[30:33]
	v_mfma_f32_16x16x32_bf16 v[26:29], v[150:153], v[202:205], v[26:29]
	v_mfma_f32_16x16x32_bf16 v[14:17], v[142:145], v[210:213], v[14:17]
	v_mfma_f32_16x16x32_bf16 v[10:13], v[150:153], v[210:213], v[10:13]
	v_mfma_f32_16x16x32_bf16 v[62:65], v[146:149], v[190:193], v[62:65]
	v_mfma_f32_16x16x32_bf16 v[58:61], v[154:157], v[190:193], v[58:61]
	v_mfma_f32_16x16x32_bf16 v[46:49], v[146:149], v[198:201], v[46:49]
	v_mfma_f32_16x16x32_bf16 v[42:45], v[154:157], v[198:201], v[42:45]
	v_mfma_f32_16x16x32_bf16 v[30:33], v[146:149], v[206:209], v[30:33]
	v_mfma_f32_16x16x32_bf16 v[26:29], v[154:157], v[206:209], v[26:29]
	v_mfma_f32_16x16x32_bf16 v[14:17], v[146:149], v[214:217], v[14:17]
	v_mfma_f32_16x16x32_bf16 v[10:13], v[154:157], v[214:217], v[10:13]
	s_barrier
	s_mov_b32 m0, s33
	s_nop 0
	global_load_lds_dwordx4 v243, s[26:27]
	s_mov_b32 m0, s34
	s_nop 0
	global_load_lds_dwordx4 v242, s[26:27]
	s_waitcnt vmcnt(6)
	s_barrier
	v_mfma_f32_16x16x32_bf16 v[54:57], v[218:221], v[186:189], v[54:57]
	v_mfma_f32_16x16x32_bf16 v[50:53], v[226:229], v[186:189], v[50:53]
	v_mfma_f32_16x16x32_bf16 v[38:41], v[218:221], v[194:197], v[38:41]
	v_mfma_f32_16x16x32_bf16 v[34:37], v[226:229], v[194:197], v[34:37]
	v_mfma_f32_16x16x32_bf16 v[22:25], v[218:221], v[202:205], v[22:25]
	v_mfma_f32_16x16x32_bf16 v[18:21], v[226:229], v[202:205], v[18:21]
	v_mfma_f32_16x16x32_bf16 v[6:9], v[218:221], v[210:213], v[6:9]
	v_mfma_f32_16x16x32_bf16 v[2:5], v[226:229], v[210:213], v[2:5]
	v_mfma_f32_16x16x32_bf16 v[54:57], v[222:225], v[190:193], v[54:57]
	v_mfma_f32_16x16x32_bf16 v[50:53], v[230:233], v[190:193], v[50:53]
	v_mfma_f32_16x16x32_bf16 v[38:41], v[222:225], v[198:201], v[38:41]
	v_mfma_f32_16x16x32_bf16 v[34:37], v[230:233], v[198:201], v[34:37]
	v_mfma_f32_16x16x32_bf16 v[22:25], v[222:225], v[206:209], v[22:25]
	v_mfma_f32_16x16x32_bf16 v[18:21], v[230:233], v[206:209], v[18:21]
	v_mfma_f32_16x16x32_bf16 v[6:9], v[222:225], v[214:217], v[6:9]
	v_mfma_f32_16x16x32_bf16 v[2:5], v[230:233], v[214:217], v[2:5]
	s_barrier
	ds_read_b128 v[142:145], v176
	ds_read_b128 v[146:149], v177
	ds_read_b128 v[150:153], v178
	ds_read_b128 v[154:157], v179
	s_mov_b32 m0, s35
	ds_read_b128 v[186:189], v166 offset:32768
	ds_read_b128 v[190:193], v166 offset:33792
	ds_read_b128 v[194:197], v166 offset:34816
	ds_read_b128 v[198:201], v166 offset:35840
	ds_read_b128 v[202:205], v166 offset:36864
	ds_read_b128 v[206:209], v166 offset:37888
	ds_read_b128 v[210:213], v166 offset:38912
	ds_read_b128 v[214:217], v166 offset:39936
	global_load_lds_dwordx4 v243, s[2:3]
	s_mov_b32 m0, s38
	s_nop 0
	global_load_lds_dwordx4 v242, s[2:3]
	s_waitcnt lgkmcnt(8)
	s_barrier
	s_waitcnt lgkmcnt(0)
	s_waitcnt lgkmcnt(0)
	v_mfma_f32_16x16x32_bf16 v[126:129], v[142:145], v[186:189], v[126:129]
	v_mfma_f32_16x16x32_bf16 v[122:125], v[150:153], v[186:189], v[122:125]
	v_mfma_f32_16x16x32_bf16 v[110:113], v[142:145], v[194:197], v[110:113]
	v_mfma_f32_16x16x32_bf16 v[106:109], v[150:153], v[194:197], v[106:109]
	v_mfma_f32_16x16x32_bf16 v[94:97], v[142:145], v[202:205], v[94:97]
	v_mfma_f32_16x16x32_bf16 v[90:93], v[150:153], v[202:205], v[90:93]
	v_mfma_f32_16x16x32_bf16 v[78:81], v[142:145], v[210:213], v[78:81]
	v_mfma_f32_16x16x32_bf16 v[74:77], v[150:153], v[210:213], v[74:77]
	v_mfma_f32_16x16x32_bf16 v[126:129], v[146:149], v[190:193], v[126:129]
	v_mfma_f32_16x16x32_bf16 v[122:125], v[154:157], v[190:193], v[122:125]
	v_mfma_f32_16x16x32_bf16 v[110:113], v[146:149], v[198:201], v[110:113]
	v_mfma_f32_16x16x32_bf16 v[106:109], v[154:157], v[198:201], v[106:109]
	v_mfma_f32_16x16x32_bf16 v[94:97], v[146:149], v[206:209], v[94:97]
	v_mfma_f32_16x16x32_bf16 v[90:93], v[154:157], v[206:209], v[90:93]
	v_mfma_f32_16x16x32_bf16 v[78:81], v[146:149], v[214:217], v[78:81]
	v_mfma_f32_16x16x32_bf16 v[74:77], v[154:157], v[214:217], v[74:77]
	s_barrier
	s_sub_u32 m0, s39, 0x80
	ds_read_b128 v[218:221], v180
	ds_read_b128 v[222:225], v181
	ds_read_b128 v[226:229], v182
	ds_read_b128 v[230:233], v183
	global_load_lds_dwordx4 v130, s[26:27] offset:128
	s_sub_u32 m0, s40, 0x80
	s_nop 0
	global_load_lds_dwordx4 v132, s[26:27] offset:128
	s_barrier
	s_waitcnt lgkmcnt(0)
	s_waitcnt lgkmcnt(0)
	v_mfma_f32_16x16x32_bf16 v[118:121], v[218:221], v[186:189], v[118:121]
	v_mfma_f32_16x16x32_bf16 v[114:117], v[226:229], v[186:189], v[114:117]
	v_mfma_f32_16x16x32_bf16 v[102:105], v[218:221], v[194:197], v[102:105]
	v_mfma_f32_16x16x32_bf16 v[98:101], v[226:229], v[194:197], v[98:101]
	v_mfma_f32_16x16x32_bf16 v[86:89], v[218:221], v[202:205], v[86:89]
	v_mfma_f32_16x16x32_bf16 v[82:85], v[226:229], v[202:205], v[82:85]
	v_mfma_f32_16x16x32_bf16 v[70:73], v[218:221], v[210:213], v[70:73]
	v_mfma_f32_16x16x32_bf16 v[66:69], v[226:229], v[210:213], v[66:69]
	v_mfma_f32_16x16x32_bf16 v[118:121], v[222:225], v[190:193], v[118:121]
	v_mfma_f32_16x16x32_bf16 v[114:117], v[230:233], v[190:193], v[114:117]
	v_mfma_f32_16x16x32_bf16 v[102:105], v[222:225], v[198:201], v[102:105]
	v_mfma_f32_16x16x32_bf16 v[98:101], v[230:233], v[198:201], v[98:101]
	v_mfma_f32_16x16x32_bf16 v[86:89], v[222:225], v[206:209], v[86:89]
	v_mfma_f32_16x16x32_bf16 v[82:85], v[230:233], v[206:209], v[82:85]
	v_mfma_f32_16x16x32_bf16 v[70:73], v[222:225], v[214:217], v[70:73]
	v_mfma_f32_16x16x32_bf16 v[66:69], v[230:233], v[214:217], v[66:69]
	s_sub_u32 m0, s41, 0x80
	s_barrier
	ds_read_b128 v[186:189], v166 offset:49152
	ds_read_b128 v[190:193], v166 offset:50176
	ds_read_b128 v[194:197], v166 offset:51200
	ds_read_b128 v[198:201], v166 offset:52224
	ds_read_b128 v[202:205], v166 offset:53248
	ds_read_b128 v[206:209], v166 offset:54272
	ds_read_b128 v[210:213], v166 offset:55296
	ds_read_b128 v[214:217], v166 offset:56320
	global_load_lds_dwordx4 v130, s[2:3] offset:128
	s_sub_u32 m0, s42, 0x80
	s_nop 0
	global_load_lds_dwordx4 v132, s[2:3] offset:128
	s_barrier
	s_waitcnt lgkmcnt(0)
	s_waitcnt lgkmcnt(0)
	v_mfma_f32_16x16x32_bf16 v[62:65], v[142:145], v[186:189], v[62:65]
	v_mfma_f32_16x16x32_bf16 v[58:61], v[150:153], v[186:189], v[58:61]
	v_mfma_f32_16x16x32_bf16 v[46:49], v[142:145], v[194:197], v[46:49]
	v_mfma_f32_16x16x32_bf16 v[42:45], v[150:153], v[194:197], v[42:45]
	v_mfma_f32_16x16x32_bf16 v[30:33], v[142:145], v[202:205], v[30:33]
	v_mfma_f32_16x16x32_bf16 v[26:29], v[150:153], v[202:205], v[26:29]
	v_mfma_f32_16x16x32_bf16 v[14:17], v[142:145], v[210:213], v[14:17]
	v_mfma_f32_16x16x32_bf16 v[10:13], v[150:153], v[210:213], v[10:13]
	v_mfma_f32_16x16x32_bf16 v[62:65], v[146:149], v[190:193], v[62:65]
	v_mfma_f32_16x16x32_bf16 v[58:61], v[154:157], v[190:193], v[58:61]
	v_mfma_f32_16x16x32_bf16 v[46:49], v[146:149], v[198:201], v[46:49]
	v_mfma_f32_16x16x32_bf16 v[42:45], v[154:157], v[198:201], v[42:45]
	v_mfma_f32_16x16x32_bf16 v[30:33], v[146:149], v[206:209], v[30:33]
	v_mfma_f32_16x16x32_bf16 v[26:29], v[154:157], v[206:209], v[26:29]
	v_mfma_f32_16x16x32_bf16 v[14:17], v[146:149], v[214:217], v[14:17]
	v_mfma_f32_16x16x32_bf16 v[10:13], v[154:157], v[214:217], v[10:13]
	s_barrier
	s_sub_u32 m0, s43, 0x80
	s_nop 0
	global_load_lds_dwordx4 v243, s[26:27] offset:128
	s_sub_u32 m0, s44, 0x80
	s_nop 0
	global_load_lds_dwordx4 v242, s[26:27] offset:128
	s_waitcnt vmcnt(6)
	s_barrier
	v_mfma_f32_16x16x32_bf16 v[54:57], v[218:221], v[186:189], v[54:57]
	v_mfma_f32_16x16x32_bf16 v[50:53], v[226:229], v[186:189], v[50:53]
	v_mfma_f32_16x16x32_bf16 v[38:41], v[218:221], v[194:197], v[38:41]
	v_mfma_f32_16x16x32_bf16 v[34:37], v[226:229], v[194:197], v[34:37]
	v_mfma_f32_16x16x32_bf16 v[22:25], v[218:221], v[202:205], v[22:25]
	v_mfma_f32_16x16x32_bf16 v[18:21], v[226:229], v[202:205], v[18:21]
	v_mfma_f32_16x16x32_bf16 v[6:9], v[218:221], v[210:213], v[6:9]
	v_mfma_f32_16x16x32_bf16 v[2:5], v[226:229], v[210:213], v[2:5]
	v_mfma_f32_16x16x32_bf16 v[54:57], v[222:225], v[190:193], v[54:57]
	v_mfma_f32_16x16x32_bf16 v[50:53], v[230:233], v[190:193], v[50:53]
	v_mfma_f32_16x16x32_bf16 v[38:41], v[222:225], v[198:201], v[38:41]
	v_mfma_f32_16x16x32_bf16 v[34:37], v[230:233], v[198:201], v[34:37]
	v_mfma_f32_16x16x32_bf16 v[22:25], v[222:225], v[206:209], v[22:25]
	v_mfma_f32_16x16x32_bf16 v[18:21], v[230:233], v[206:209], v[18:21]
	v_mfma_f32_16x16x32_bf16 v[6:9], v[222:225], v[214:217], v[6:9]
	v_mfma_f32_16x16x32_bf16 v[2:5], v[230:233], v[214:217], v[2:5]
	s_add_u32 s24, s24, 0x100
	s_addc_u32 s25, s25, 0
	s_add_u32 s36, s36, 0x100
	s_addc_u32 s37, s37, 0
	s_cmp_ge_i32 s57, s45
	s_mov_b32 s2, s57
	s_barrier
	s_cbranch_scc0 .LBB0_997

.LBB0_1104:
	ds_read_b128 v[122:125], v185
	ds_read_b128 v[126:129], v186
	ds_read_b128 v[138:141], v187
	ds_read_b128 v[142:145], v188
	s_mov_b32 m0, s61
	ds_read_b128 v[146:149], v183
	ds_read_b128 v[150:153], v183 offset:1024
	ds_read_b128 v[154:157], v183 offset:2048
	ds_read_b128 v[158:161], v183 offset:3072
	ds_read_b128 v[176:179], v183 offset:4096
	ds_read_b128 v[202:205], v183 offset:5120
	ds_read_b128 v[206:209], v183 offset:6144
	ds_read_b128 v[210:213], v183 offset:7168
	global_load_lds_dwordx4 v168, s[0:1]
	s_mov_b32 m0, s62
	s_nop 0
	global_load_lds_dwordx4 v170, s[0:1]
	s_add_i32 s36, s2, 2
	s_add_u32 s26, s0, 0x80
	s_addc_u32 s3, s1, 0
	s_cmp_eq_u32 s58, s2
	s_cselect_b32 s2, s8, s26
	s_cselect_b32 s3, s9, s3
	s_cselect_b32 s27, s55, s29
	s_cselect_b32 s26, s54, s28
	s_waitcnt lgkmcnt(8)
	s_barrier
	s_waitcnt lgkmcnt(0)
	s_waitcnt lgkmcnt(0)
	v_mfma_f32_16x16x32_bf16 v[134:137], v[122:125], v[146:149], v[134:137]
	v_mfma_f32_16x16x32_bf16 v[118:121], v[138:141], v[146:149], v[118:121]
	v_mfma_f32_16x16x32_bf16 v[110:113], v[122:125], v[154:157], v[110:113]
	v_mfma_f32_16x16x32_bf16 v[102:105], v[138:141], v[154:157], v[102:105]
	v_mfma_f32_16x16x32_bf16 v[94:97], v[122:125], v[176:179], v[94:97]
	v_mfma_f32_16x16x32_bf16 v[86:89], v[138:141], v[176:179], v[86:89]
	v_mfma_f32_16x16x32_bf16 v[78:81], v[122:125], v[206:209], v[78:81]
	v_mfma_f32_16x16x32_bf16 v[70:73], v[138:141], v[206:209], v[70:73]
	v_mfma_f32_16x16x32_bf16 v[134:137], v[126:129], v[150:153], v[134:137]
	v_mfma_f32_16x16x32_bf16 v[118:121], v[142:145], v[150:153], v[118:121]
	v_mfma_f32_16x16x32_bf16 v[110:113], v[126:129], v[158:161], v[110:113]
	v_mfma_f32_16x16x32_bf16 v[102:105], v[142:145], v[158:161], v[102:105]
	v_mfma_f32_16x16x32_bf16 v[94:97], v[126:129], v[202:205], v[94:97]
	v_mfma_f32_16x16x32_bf16 v[86:89], v[142:145], v[202:205], v[86:89]
	v_mfma_f32_16x16x32_bf16 v[78:81], v[126:129], v[210:213], v[78:81]
	v_mfma_f32_16x16x32_bf16 v[70:73], v[142:145], v[210:213], v[70:73]
	s_barrier
	s_mov_b32 m0, s35
	ds_read_b128 v[214:217], v189
	ds_read_b128 v[218:221], v190
	ds_read_b128 v[222:225], v191
	ds_read_b128 v[226:229], v192
	global_load_lds_dwordx4 v166, s[26:27]
	s_mov_b32 m0, s38
	s_nop 0
	global_load_lds_dwordx4 v164, s[26:27]
	s_barrier
	s_waitcnt lgkmcnt(0)
	s_waitcnt lgkmcnt(0)
	v_mfma_f32_16x16x32_bf16 v[130:133], v[214:217], v[146:149], v[130:133]
	v_mfma_f32_16x16x32_bf16 v[114:117], v[222:225], v[146:149], v[114:117]
	v_mfma_f32_16x16x32_bf16 v[106:109], v[214:217], v[154:157], v[106:109]
	v_mfma_f32_16x16x32_bf16 v[98:101], v[222:225], v[154:157], v[98:101]
	v_mfma_f32_16x16x32_bf16 v[90:93], v[214:217], v[176:179], v[90:93]
	v_mfma_f32_16x16x32_bf16 v[82:85], v[222:225], v[176:179], v[82:85]
	v_mfma_f32_16x16x32_bf16 v[74:77], v[214:217], v[206:209], v[74:77]
	v_mfma_f32_16x16x32_bf16 v[66:69], v[222:225], v[206:209], v[66:69]
	v_mfma_f32_16x16x32_bf16 v[130:133], v[218:221], v[150:153], v[130:133]
	v_mfma_f32_16x16x32_bf16 v[114:117], v[226:229], v[150:153], v[114:117]
	v_mfma_f32_16x16x32_bf16 v[106:109], v[218:221], v[158:161], v[106:109]
	v_mfma_f32_16x16x32_bf16 v[98:101], v[226:229], v[158:161], v[98:101]
	v_mfma_f32_16x16x32_bf16 v[90:93], v[218:221], v[202:205], v[90:93]
	v_mfma_f32_16x16x32_bf16 v[82:85], v[226:229], v[202:205], v[82:85]
	v_mfma_f32_16x16x32_bf16 v[74:77], v[218:221], v[210:213], v[74:77]
	v_mfma_f32_16x16x32_bf16 v[66:69], v[226:229], v[210:213], v[66:69]
	s_mov_b32 m0, s31
	s_barrier
	ds_read_b128 v[146:149], v183 offset:16384
	ds_read_b128 v[150:153], v183 offset:17408
	ds_read_b128 v[154:157], v183 offset:18432
	ds_read_b128 v[158:161], v183 offset:19456
	ds_read_b128 v[176:179], v183 offset:20480
	ds_read_b128 v[202:205], v183 offset:21504
	ds_read_b128 v[206:209], v183 offset:22528
	ds_read_b128 v[210:213], v183 offset:23552
	global_load_lds_dwordx4 v166, s[2:3]
	s_mov_b32 m0, s39
	s_nop 0
	global_load_lds_dwordx4 v164, s[2:3]
	s_barrier
	s_waitcnt lgkmcnt(0)
	s_waitcnt lgkmcnt(0)
	v_mfma_f32_16x16x32_bf16 v[62:65], v[122:125], v[146:149], v[62:65]
	v_mfma_f32_16x16x32_bf16 v[54:57], v[138:141], v[146:149], v[54:57]
	v_mfma_f32_16x16x32_bf16 v[46:49], v[122:125], v[154:157], v[46:49]
	v_mfma_f32_16x16x32_bf16 v[38:41], v[138:141], v[154:157], v[38:41]
	v_mfma_f32_16x16x32_bf16 v[30:33], v[122:125], v[176:179], v[30:33]
	v_mfma_f32_16x16x32_bf16 v[22:25], v[138:141], v[176:179], v[22:25]
	v_mfma_f32_16x16x32_bf16 v[14:17], v[122:125], v[206:209], v[14:17]
	v_mfma_f32_16x16x32_bf16 v[6:9], v[138:141], v[206:209], v[6:9]
	v_mfma_f32_16x16x32_bf16 v[62:65], v[126:129], v[150:153], v[62:65]
	v_mfma_f32_16x16x32_bf16 v[54:57], v[142:145], v[150:153], v[54:57]
	v_mfma_f32_16x16x32_bf16 v[46:49], v[126:129], v[158:161], v[46:49]
	v_mfma_f32_16x16x32_bf16 v[38:41], v[142:145], v[158:161], v[38:41]
	v_mfma_f32_16x16x32_bf16 v[30:33], v[126:129], v[202:205], v[30:33]
	v_mfma_f32_16x16x32_bf16 v[22:25], v[142:145], v[202:205], v[22:25]
	v_mfma_f32_16x16x32_bf16 v[14:17], v[126:129], v[210:213], v[14:17]
	v_mfma_f32_16x16x32_bf16 v[6:9], v[142:145], v[210:213], v[6:9]
	s_barrier
	s_mov_b32 m0, s40
	s_nop 0
	global_load_lds_dwordx4 v240, s[26:27]
	s_mov_b32 m0, s41
	s_nop 0
	global_load_lds_dwordx4 v241, s[26:27]
	s_waitcnt vmcnt(6)
	s_barrier
	v_mfma_f32_16x16x32_bf16 v[58:61], v[214:217], v[146:149], v[58:61]
	v_mfma_f32_16x16x32_bf16 v[50:53], v[222:225], v[146:149], v[50:53]
	v_mfma_f32_16x16x32_bf16 v[42:45], v[214:217], v[154:157], v[42:45]
	v_mfma_f32_16x16x32_bf16 v[34:37], v[222:225], v[154:157], v[34:37]
	v_mfma_f32_16x16x32_bf16 v[26:29], v[214:217], v[176:179], v[26:29]
	v_mfma_f32_16x16x32_bf16 v[18:21], v[222:225], v[176:179], v[18:21]
	v_mfma_f32_16x16x32_bf16 v[10:13], v[214:217], v[206:209], v[10:13]
	v_mfma_f32_16x16x32_bf16 v[2:5], v[222:225], v[206:209], v[2:5]
	v_mfma_f32_16x16x32_bf16 v[58:61], v[218:221], v[150:153], v[58:61]
	v_mfma_f32_16x16x32_bf16 v[50:53], v[226:229], v[150:153], v[50:53]
	v_mfma_f32_16x16x32_bf16 v[42:45], v[218:221], v[158:161], v[42:45]
	v_mfma_f32_16x16x32_bf16 v[34:37], v[226:229], v[158:161], v[34:37]
	v_mfma_f32_16x16x32_bf16 v[26:29], v[218:221], v[202:205], v[26:29]
	v_mfma_f32_16x16x32_bf16 v[18:21], v[226:229], v[202:205], v[18:21]
	v_mfma_f32_16x16x32_bf16 v[10:13], v[218:221], v[210:213], v[10:13]
	v_mfma_f32_16x16x32_bf16 v[2:5], v[226:229], v[210:213], v[2:5]
	s_barrier
	ds_read_b128 v[122:125], v193
	ds_read_b128 v[126:129], v194
	ds_read_b128 v[138:141], v195
	ds_read_b128 v[142:145], v196
	s_mov_b32 m0, s42
	ds_read_b128 v[146:149], v183 offset:32768
	ds_read_b128 v[150:153], v183 offset:33792
	ds_read_b128 v[154:157], v183 offset:34816
	ds_read_b128 v[158:161], v183 offset:35840
	ds_read_b128 v[176:179], v183 offset:36864
	ds_read_b128 v[202:205], v183 offset:37888
	ds_read_b128 v[206:209], v183 offset:38912
	ds_read_b128 v[210:213], v183 offset:39936
	global_load_lds_dwordx4 v240, s[2:3]
	s_mov_b32 m0, s43
	s_nop 0
	global_load_lds_dwordx4 v241, s[2:3]
	s_waitcnt lgkmcnt(8)
	s_barrier
	s_waitcnt lgkmcnt(0)
	s_waitcnt lgkmcnt(0)
	v_mfma_f32_16x16x32_bf16 v[134:137], v[122:125], v[146:149], v[134:137]
	v_mfma_f32_16x16x32_bf16 v[118:121], v[138:141], v[146:149], v[118:121]
	v_mfma_f32_16x16x32_bf16 v[110:113], v[122:125], v[154:157], v[110:113]
	v_mfma_f32_16x16x32_bf16 v[102:105], v[138:141], v[154:157], v[102:105]
	v_mfma_f32_16x16x32_bf16 v[94:97], v[122:125], v[176:179], v[94:97]
	v_mfma_f32_16x16x32_bf16 v[86:89], v[138:141], v[176:179], v[86:89]
	v_mfma_f32_16x16x32_bf16 v[78:81], v[122:125], v[206:209], v[78:81]
	v_mfma_f32_16x16x32_bf16 v[70:73], v[138:141], v[206:209], v[70:73]
	v_mfma_f32_16x16x32_bf16 v[134:137], v[126:129], v[150:153], v[134:137]
	v_mfma_f32_16x16x32_bf16 v[118:121], v[142:145], v[150:153], v[118:121]
	v_mfma_f32_16x16x32_bf16 v[110:113], v[126:129], v[158:161], v[110:113]
	v_mfma_f32_16x16x32_bf16 v[102:105], v[142:145], v[158:161], v[102:105]
	v_mfma_f32_16x16x32_bf16 v[94:97], v[126:129], v[202:205], v[94:97]
	v_mfma_f32_16x16x32_bf16 v[86:89], v[142:145], v[202:205], v[86:89]
	v_mfma_f32_16x16x32_bf16 v[78:81], v[126:129], v[210:213], v[78:81]
	v_mfma_f32_16x16x32_bf16 v[70:73], v[142:145], v[210:213], v[70:73]
	s_barrier
	s_sub_u32 m0, s48, 0x80
	ds_read_b128 v[214:217], v197
	ds_read_b128 v[218:221], v198
	ds_read_b128 v[222:225], v199
	ds_read_b128 v[226:229], v200
	global_load_lds_dwordx4 v166, s[26:27] offset:128
	s_sub_u32 m0, s49, 0x80
	s_nop 0
	global_load_lds_dwordx4 v164, s[26:27] offset:128
	s_barrier
	s_waitcnt lgkmcnt(0)
	s_waitcnt lgkmcnt(0)
	v_mfma_f32_16x16x32_bf16 v[130:133], v[214:217], v[146:149], v[130:133]
	v_mfma_f32_16x16x32_bf16 v[114:117], v[222:225], v[146:149], v[114:117]
	v_mfma_f32_16x16x32_bf16 v[106:109], v[214:217], v[154:157], v[106:109]
	v_mfma_f32_16x16x32_bf16 v[98:101], v[222:225], v[154:157], v[98:101]
	v_mfma_f32_16x16x32_bf16 v[90:93], v[214:217], v[176:179], v[90:93]
	v_mfma_f32_16x16x32_bf16 v[82:85], v[222:225], v[176:179], v[82:85]
	v_mfma_f32_16x16x32_bf16 v[74:77], v[214:217], v[206:209], v[74:77]
	v_mfma_f32_16x16x32_bf16 v[66:69], v[222:225], v[206:209], v[66:69]
	v_mfma_f32_16x16x32_bf16 v[130:133], v[218:221], v[150:153], v[130:133]
	v_mfma_f32_16x16x32_bf16 v[114:117], v[226:229], v[150:153], v[114:117]
	v_mfma_f32_16x16x32_bf16 v[106:109], v[218:221], v[158:161], v[106:109]
	v_mfma_f32_16x16x32_bf16 v[98:101], v[226:229], v[158:161], v[98:101]
	v_mfma_f32_16x16x32_bf16 v[90:93], v[218:221], v[202:205], v[90:93]
	v_mfma_f32_16x16x32_bf16 v[82:85], v[226:229], v[202:205], v[82:85]
	v_mfma_f32_16x16x32_bf16 v[74:77], v[218:221], v[210:213], v[74:77]
	v_mfma_f32_16x16x32_bf16 v[66:69], v[226:229], v[210:213], v[66:69]
	s_sub_u32 m0, s50, 0x80
	s_barrier
	ds_read_b128 v[146:149], v183 offset:49152
	ds_read_b128 v[150:153], v183 offset:50176
	ds_read_b128 v[154:157], v183 offset:51200
	ds_read_b128 v[158:161], v183 offset:52224
	ds_read_b128 v[176:179], v183 offset:53248
	ds_read_b128 v[202:205], v183 offset:54272
	ds_read_b128 v[206:209], v183 offset:55296
	ds_read_b128 v[210:213], v183 offset:56320
	global_load_lds_dwordx4 v166, s[2:3] offset:128
	s_sub_u32 m0, s51, 0x80
	s_nop 0
	global_load_lds_dwordx4 v164, s[2:3] offset:128
	s_barrier
	s_waitcnt lgkmcnt(0)
	s_waitcnt lgkmcnt(0)
	v_mfma_f32_16x16x32_bf16 v[62:65], v[122:125], v[146:149], v[62:65]
	v_mfma_f32_16x16x32_bf16 v[54:57], v[138:141], v[146:149], v[54:57]
	v_mfma_f32_16x16x32_bf16 v[46:49], v[122:125], v[154:157], v[46:49]
	v_mfma_f32_16x16x32_bf16 v[38:41], v[138:141], v[154:157], v[38:41]
	v_mfma_f32_16x16x32_bf16 v[30:33], v[122:125], v[176:179], v[30:33]
	v_mfma_f32_16x16x32_bf16 v[22:25], v[138:141], v[176:179], v[22:25]
	v_mfma_f32_16x16x32_bf16 v[14:17], v[122:125], v[206:209], v[14:17]
	v_mfma_f32_16x16x32_bf16 v[6:9], v[138:141], v[206:209], v[6:9]
	v_mfma_f32_16x16x32_bf16 v[62:65], v[126:129], v[150:153], v[62:65]
	v_mfma_f32_16x16x32_bf16 v[54:57], v[142:145], v[150:153], v[54:57]
	v_mfma_f32_16x16x32_bf16 v[46:49], v[126:129], v[158:161], v[46:49]
	v_mfma_f32_16x16x32_bf16 v[38:41], v[142:145], v[158:161], v[38:41]
	v_mfma_f32_16x16x32_bf16 v[30:33], v[126:129], v[202:205], v[30:33]
	v_mfma_f32_16x16x32_bf16 v[22:25], v[142:145], v[202:205], v[22:25]
	v_mfma_f32_16x16x32_bf16 v[14:17], v[126:129], v[210:213], v[14:17]
	v_mfma_f32_16x16x32_bf16 v[6:9], v[142:145], v[210:213], v[6:9]
	s_barrier
	s_sub_u32 m0, s53, 0x80
	s_nop 0
	global_load_lds_dwordx4 v240, s[26:27] offset:128
	s_sub_u32 m0, s56, 0x80
	s_nop 0
	global_load_lds_dwordx4 v241, s[26:27] offset:128
	s_waitcnt vmcnt(6)
	s_barrier
	v_mfma_f32_16x16x32_bf16 v[58:61], v[214:217], v[146:149], v[58:61]
	v_mfma_f32_16x16x32_bf16 v[50:53], v[222:225], v[146:149], v[50:53]
	v_mfma_f32_16x16x32_bf16 v[42:45], v[214:217], v[154:157], v[42:45]
	v_mfma_f32_16x16x32_bf16 v[34:37], v[222:225], v[154:157], v[34:37]
	v_mfma_f32_16x16x32_bf16 v[26:29], v[214:217], v[176:179], v[26:29]
	v_mfma_f32_16x16x32_bf16 v[18:21], v[222:225], v[176:179], v[18:21]
	v_mfma_f32_16x16x32_bf16 v[10:13], v[214:217], v[206:209], v[10:13]
	v_mfma_f32_16x16x32_bf16 v[2:5], v[222:225], v[206:209], v[2:5]
	v_mfma_f32_16x16x32_bf16 v[58:61], v[218:221], v[150:153], v[58:61]
	v_mfma_f32_16x16x32_bf16 v[50:53], v[226:229], v[150:153], v[50:53]
	v_mfma_f32_16x16x32_bf16 v[42:45], v[218:221], v[158:161], v[42:45]
	v_mfma_f32_16x16x32_bf16 v[34:37], v[226:229], v[158:161], v[34:37]
	v_mfma_f32_16x16x32_bf16 v[26:29], v[218:221], v[202:205], v[26:29]
	v_mfma_f32_16x16x32_bf16 v[18:21], v[226:229], v[202:205], v[18:21]
	v_mfma_f32_16x16x32_bf16 v[10:13], v[218:221], v[210:213], v[10:13]
	v_mfma_f32_16x16x32_bf16 v[2:5], v[226:229], v[210:213], v[2:5]
	s_add_u32 s0, s0, 0x100
	s_addc_u32 s1, s1, 0
	s_add_u32 s28, s28, 0x100
	s_addc_u32 s29, s29, 0
	s_cmp_ge_i32 s36, s57
	s_mov_b32 s2, s36
	s_barrier
	s_cbranch_scc0 .LBB0_1104
	s_branch .LBB0_1095

.LBB0_1255:
	ds_read_b128 v[146:149], v177
	ds_read_b128 v[150:153], v178
	ds_read_b128 v[154:157], v179
	ds_read_b128 v[158:161], v180
	s_mov_b32 m0, s66
	ds_read_b128 v[164:167], v174
	ds_read_b128 v[168:171], v174 offset:1024
	ds_read_b128 v[194:197], v174 offset:2048
	ds_read_b128 v[198:201], v174 offset:3072
	ds_read_b128 v[206:209], v174 offset:4096
	ds_read_b128 v[210:213], v174 offset:5120
	ds_read_b128 v[214:217], v174 offset:6144
	ds_read_b128 v[218:221], v174 offset:7168
	global_load_lds_dwordx4 v138, s[26:27]
	s_mov_b32 m0, s67
	s_nop 0
	global_load_lds_dwordx4 v140, s[26:27]
	s_add_i32 s72, s2, 2
	s_add_u32 s28, s26, 0x80
	s_addc_u32 s3, s27, 0
	s_cmp_eq_u32 s64, s2
	s_cselect_b32 s2, s54, s28
	s_cselect_b32 s3, s55, s3
	s_cselect_b32 s29, s1, s53
	s_cselect_b32 s28, s0, s37
	s_waitcnt lgkmcnt(8)
	s_barrier
	s_waitcnt lgkmcnt(0)
	s_waitcnt lgkmcnt(0)
	v_mfma_f32_16x16x32_bf16 v[130:133], v[146:149], v[164:167], v[130:133]
	v_mfma_f32_16x16x32_bf16 v[126:129], v[154:157], v[164:167], v[126:129]
	v_mfma_f32_16x16x32_bf16 v[114:117], v[146:149], v[194:197], v[114:117]
	v_mfma_f32_16x16x32_bf16 v[110:113], v[154:157], v[194:197], v[110:113]
	v_mfma_f32_16x16x32_bf16 v[98:101], v[146:149], v[206:209], v[98:101]
	v_mfma_f32_16x16x32_bf16 v[94:97], v[154:157], v[206:209], v[94:97]
	v_mfma_f32_16x16x32_bf16 v[82:85], v[146:149], v[214:217], v[82:85]
	v_mfma_f32_16x16x32_bf16 v[78:81], v[154:157], v[214:217], v[78:81]
	v_mfma_f32_16x16x32_bf16 v[130:133], v[150:153], v[168:171], v[130:133]
	v_mfma_f32_16x16x32_bf16 v[126:129], v[158:161], v[168:171], v[126:129]
	v_mfma_f32_16x16x32_bf16 v[114:117], v[150:153], v[198:201], v[114:117]
	v_mfma_f32_16x16x32_bf16 v[110:113], v[158:161], v[198:201], v[110:113]
	v_mfma_f32_16x16x32_bf16 v[98:101], v[150:153], v[210:213], v[98:101]
	v_mfma_f32_16x16x32_bf16 v[94:97], v[158:161], v[210:213], v[94:97]
	v_mfma_f32_16x16x32_bf16 v[82:85], v[150:153], v[218:221], v[82:85]
	v_mfma_f32_16x16x32_bf16 v[78:81], v[158:161], v[218:221], v[78:81]
	s_barrier
	s_mov_b32 m0, s38
	ds_read_b128 v[222:225], v181
	ds_read_b128 v[226:229], v182
	ds_read_b128 v[230:233], v183
	ds_read_b128 v[234:237], v184
	global_load_lds_dwordx4 v134, s[28:29]
	s_mov_b32 m0, s39
	s_nop 0
	global_load_lds_dwordx4 v136, s[28:29]
	s_barrier
	s_waitcnt lgkmcnt(0)
	s_waitcnt lgkmcnt(0)
	v_mfma_f32_16x16x32_bf16 v[122:125], v[222:225], v[164:167], v[122:125]
	v_mfma_f32_16x16x32_bf16 v[118:121], v[230:233], v[164:167], v[118:121]
	v_mfma_f32_16x16x32_bf16 v[106:109], v[222:225], v[194:197], v[106:109]
	v_mfma_f32_16x16x32_bf16 v[102:105], v[230:233], v[194:197], v[102:105]
	v_mfma_f32_16x16x32_bf16 v[90:93], v[222:225], v[206:209], v[90:93]
	v_mfma_f32_16x16x32_bf16 v[86:89], v[230:233], v[206:209], v[86:89]
	v_mfma_f32_16x16x32_bf16 v[74:77], v[222:225], v[214:217], v[74:77]
	v_mfma_f32_16x16x32_bf16 v[68:71], v[230:233], v[214:217], v[70:73]
	v_mfma_f32_16x16x32_bf16 v[122:125], v[226:229], v[168:171], v[122:125]
	v_mfma_f32_16x16x32_bf16 v[118:121], v[234:237], v[168:171], v[118:121]
	v_mfma_f32_16x16x32_bf16 v[106:109], v[226:229], v[198:201], v[106:109]
	v_mfma_f32_16x16x32_bf16 v[102:105], v[234:237], v[198:201], v[102:105]
	v_mfma_f32_16x16x32_bf16 v[90:93], v[226:229], v[210:213], v[90:93]
	v_mfma_f32_16x16x32_bf16 v[86:89], v[234:237], v[210:213], v[86:89]
	v_mfma_f32_16x16x32_bf16 v[74:77], v[226:229], v[218:221], v[74:77]
	v_mfma_f32_16x16x32_bf16 v[68:71], v[234:237], v[218:221], v[68:71]
	s_mov_b32 m0, s35
	s_barrier
	ds_read_b128 v[164:167], v174 offset:16384
	ds_read_b128 v[168:171], v174 offset:17408
	ds_read_b128 v[194:197], v174 offset:18432
	ds_read_b128 v[198:201], v174 offset:19456
	ds_read_b128 v[206:209], v174 offset:20480
	ds_read_b128 v[210:213], v174 offset:21504
	ds_read_b128 v[214:217], v174 offset:22528
	ds_read_b128 v[218:221], v174 offset:23552
	global_load_lds_dwordx4 v134, s[2:3]
	s_mov_b32 m0, s40
	s_nop 0
	global_load_lds_dwordx4 v136, s[2:3]
	s_barrier
	s_waitcnt lgkmcnt(0)
	s_waitcnt lgkmcnt(0)
	v_mfma_f32_16x16x32_bf16 v[62:65], v[146:149], v[164:167], v[62:65]
	v_mfma_f32_16x16x32_bf16 v[58:61], v[154:157], v[164:167], v[58:61]
	v_mfma_f32_16x16x32_bf16 v[46:49], v[146:149], v[194:197], v[46:49]
	v_mfma_f32_16x16x32_bf16 v[42:45], v[154:157], v[194:197], v[42:45]
	v_mfma_f32_16x16x32_bf16 v[30:33], v[146:149], v[206:209], v[30:33]
	v_mfma_f32_16x16x32_bf16 v[26:29], v[154:157], v[206:209], v[26:29]
	v_mfma_f32_16x16x32_bf16 v[14:17], v[146:149], v[214:217], v[14:17]
	v_mfma_f32_16x16x32_bf16 v[10:13], v[154:157], v[214:217], v[10:13]
	v_mfma_f32_16x16x32_bf16 v[62:65], v[150:153], v[168:171], v[62:65]
	v_mfma_f32_16x16x32_bf16 v[58:61], v[158:161], v[168:171], v[58:61]
	v_mfma_f32_16x16x32_bf16 v[46:49], v[150:153], v[198:201], v[46:49]
	v_mfma_f32_16x16x32_bf16 v[42:45], v[158:161], v[198:201], v[42:45]
	v_mfma_f32_16x16x32_bf16 v[30:33], v[150:153], v[210:213], v[30:33]
	v_mfma_f32_16x16x32_bf16 v[26:29], v[158:161], v[210:213], v[26:29]
	v_mfma_f32_16x16x32_bf16 v[14:17], v[150:153], v[218:221], v[14:17]
	v_mfma_f32_16x16x32_bf16 v[10:13], v[158:161], v[218:221], v[10:13]
	s_barrier
	s_mov_b32 m0, s41
	s_nop 0
	global_load_lds_dwordx4 v249, s[28:29]
	s_mov_b32 m0, s42
	s_nop 0
	global_load_lds_dwordx4 v248, s[28:29]
	s_waitcnt vmcnt(6)
	s_barrier
	v_mfma_f32_16x16x32_bf16 v[54:57], v[222:225], v[164:167], v[54:57]
	v_mfma_f32_16x16x32_bf16 v[50:53], v[230:233], v[164:167], v[50:53]
	v_mfma_f32_16x16x32_bf16 v[38:41], v[222:225], v[194:197], v[38:41]
	v_mfma_f32_16x16x32_bf16 v[34:37], v[230:233], v[194:197], v[34:37]
	v_mfma_f32_16x16x32_bf16 v[22:25], v[222:225], v[206:209], v[22:25]
	v_mfma_f32_16x16x32_bf16 v[18:21], v[230:233], v[206:209], v[18:21]
	v_mfma_f32_16x16x32_bf16 v[6:9], v[222:225], v[214:217], v[6:9]
	v_mfma_f32_16x16x32_bf16 v[2:5], v[230:233], v[214:217], v[2:5]
	v_mfma_f32_16x16x32_bf16 v[54:57], v[226:229], v[168:171], v[54:57]
	v_mfma_f32_16x16x32_bf16 v[50:53], v[234:237], v[168:171], v[50:53]
	v_mfma_f32_16x16x32_bf16 v[38:41], v[226:229], v[198:201], v[38:41]
	v_mfma_f32_16x16x32_bf16 v[34:37], v[234:237], v[198:201], v[34:37]
	v_mfma_f32_16x16x32_bf16 v[22:25], v[226:229], v[210:213], v[22:25]
	v_mfma_f32_16x16x32_bf16 v[18:21], v[234:237], v[210:213], v[18:21]
	v_mfma_f32_16x16x32_bf16 v[6:9], v[226:229], v[218:221], v[6:9]
	v_mfma_f32_16x16x32_bf16 v[2:5], v[234:237], v[218:221], v[2:5]
	s_barrier
	ds_read_b128 v[146:149], v185
	ds_read_b128 v[150:153], v186
	ds_read_b128 v[154:157], v187
	ds_read_b128 v[158:161], v188
	s_mov_b32 m0, s43
	ds_read_b128 v[164:167], v174 offset:32768
	ds_read_b128 v[168:171], v174 offset:33792
	ds_read_b128 v[194:197], v174 offset:34816
	ds_read_b128 v[198:201], v174 offset:35840
	ds_read_b128 v[206:209], v174 offset:36864
	ds_read_b128 v[210:213], v174 offset:37888
	ds_read_b128 v[214:217], v174 offset:38912
	ds_read_b128 v[218:221], v174 offset:39936
	global_load_lds_dwordx4 v249, s[2:3]
	s_mov_b32 m0, s45
	s_nop 0
	global_load_lds_dwordx4 v248, s[2:3]
	s_waitcnt lgkmcnt(8)
	s_barrier
	s_waitcnt lgkmcnt(0)
	s_waitcnt lgkmcnt(0)
	v_mfma_f32_16x16x32_bf16 v[130:133], v[146:149], v[164:167], v[130:133]
	v_mfma_f32_16x16x32_bf16 v[126:129], v[154:157], v[164:167], v[126:129]
	v_mfma_f32_16x16x32_bf16 v[114:117], v[146:149], v[194:197], v[114:117]
	v_mfma_f32_16x16x32_bf16 v[110:113], v[154:157], v[194:197], v[110:113]
	v_mfma_f32_16x16x32_bf16 v[98:101], v[146:149], v[206:209], v[98:101]
	v_mfma_f32_16x16x32_bf16 v[94:97], v[154:157], v[206:209], v[94:97]
	v_mfma_f32_16x16x32_bf16 v[82:85], v[146:149], v[214:217], v[82:85]
	v_mfma_f32_16x16x32_bf16 v[78:81], v[154:157], v[214:217], v[78:81]
	v_mfma_f32_16x16x32_bf16 v[130:133], v[150:153], v[168:171], v[130:133]
	v_mfma_f32_16x16x32_bf16 v[126:129], v[158:161], v[168:171], v[126:129]
	v_mfma_f32_16x16x32_bf16 v[114:117], v[150:153], v[198:201], v[114:117]
	v_mfma_f32_16x16x32_bf16 v[110:113], v[158:161], v[198:201], v[110:113]
	v_mfma_f32_16x16x32_bf16 v[98:101], v[150:153], v[210:213], v[98:101]
	v_mfma_f32_16x16x32_bf16 v[94:97], v[158:161], v[210:213], v[94:97]
	v_mfma_f32_16x16x32_bf16 v[82:85], v[150:153], v[218:221], v[82:85]
	v_mfma_f32_16x16x32_bf16 v[78:81], v[158:161], v[218:221], v[78:81]
	s_barrier
	s_sub_u32 m0, s50, 0x80
	ds_read_b128 v[222:225], v189
	ds_read_b128 v[226:229], v190
	ds_read_b128 v[230:233], v191
	ds_read_b128 v[234:237], v192
	global_load_lds_dwordx4 v134, s[28:29] offset:128
	s_sub_u32 m0, s51, 0x80
	s_nop 0
	global_load_lds_dwordx4 v136, s[28:29] offset:128
	s_barrier
	s_waitcnt lgkmcnt(0)
	s_waitcnt lgkmcnt(0)
	v_mfma_f32_16x16x32_bf16 v[122:125], v[222:225], v[164:167], v[122:125]
	v_mfma_f32_16x16x32_bf16 v[118:121], v[230:233], v[164:167], v[118:121]
	v_mfma_f32_16x16x32_bf16 v[106:109], v[222:225], v[194:197], v[106:109]
	v_mfma_f32_16x16x32_bf16 v[102:105], v[230:233], v[194:197], v[102:105]
	v_mfma_f32_16x16x32_bf16 v[90:93], v[222:225], v[206:209], v[90:93]
	v_mfma_f32_16x16x32_bf16 v[86:89], v[230:233], v[206:209], v[86:89]
	v_mfma_f32_16x16x32_bf16 v[72:75], v[222:225], v[214:217], v[74:77]
	v_mfma_f32_16x16x32_bf16 v[68:71], v[230:233], v[214:217], v[68:71]
	v_mfma_f32_16x16x32_bf16 v[122:125], v[226:229], v[168:171], v[122:125]
	v_mfma_f32_16x16x32_bf16 v[118:121], v[234:237], v[168:171], v[118:121]
	v_mfma_f32_16x16x32_bf16 v[106:109], v[226:229], v[198:201], v[106:109]
	v_mfma_f32_16x16x32_bf16 v[102:105], v[234:237], v[198:201], v[102:105]
	v_mfma_f32_16x16x32_bf16 v[90:93], v[226:229], v[210:213], v[90:93]
	v_mfma_f32_16x16x32_bf16 v[86:89], v[234:237], v[210:213], v[86:89]
	v_mfma_f32_16x16x32_bf16 v[74:77], v[226:229], v[218:221], v[72:75]
	v_mfma_f32_16x16x32_bf16 v[70:73], v[234:237], v[218:221], v[68:71]
	s_sub_u32 m0, s60, 0x80
	s_nop 0
	s_barrier
	ds_read_b128 v[164:167], v174 offset:49152
	ds_read_b128 v[168:171], v174 offset:50176
	ds_read_b128 v[194:197], v174 offset:51200
	ds_read_b128 v[198:201], v174 offset:52224
	ds_read_b128 v[206:209], v174 offset:53248
	ds_read_b128 v[210:213], v174 offset:54272
	ds_read_b128 v[214:217], v174 offset:55296
	ds_read_b128 v[218:221], v174 offset:56320
	global_load_lds_dwordx4 v134, s[2:3] offset:128
	s_sub_u32 m0, s61, 0x80
	s_nop 0
	global_load_lds_dwordx4 v136, s[2:3] offset:128
	s_barrier
	s_waitcnt lgkmcnt(0)
	s_waitcnt lgkmcnt(0)
	v_mfma_f32_16x16x32_bf16 v[62:65], v[146:149], v[164:167], v[62:65]
	v_mfma_f32_16x16x32_bf16 v[58:61], v[154:157], v[164:167], v[58:61]
	v_mfma_f32_16x16x32_bf16 v[46:49], v[146:149], v[194:197], v[46:49]
	v_mfma_f32_16x16x32_bf16 v[42:45], v[154:157], v[194:197], v[42:45]
	v_mfma_f32_16x16x32_bf16 v[30:33], v[146:149], v[206:209], v[30:33]
	v_mfma_f32_16x16x32_bf16 v[26:29], v[154:157], v[206:209], v[26:29]
	v_mfma_f32_16x16x32_bf16 v[14:17], v[146:149], v[214:217], v[14:17]
	v_mfma_f32_16x16x32_bf16 v[10:13], v[154:157], v[214:217], v[10:13]
	v_mfma_f32_16x16x32_bf16 v[62:65], v[150:153], v[168:171], v[62:65]
	v_mfma_f32_16x16x32_bf16 v[58:61], v[158:161], v[168:171], v[58:61]
	v_mfma_f32_16x16x32_bf16 v[46:49], v[150:153], v[198:201], v[46:49]
	v_mfma_f32_16x16x32_bf16 v[42:45], v[158:161], v[198:201], v[42:45]
	v_mfma_f32_16x16x32_bf16 v[30:33], v[150:153], v[210:213], v[30:33]
	v_mfma_f32_16x16x32_bf16 v[26:29], v[158:161], v[210:213], v[26:29]
	v_mfma_f32_16x16x32_bf16 v[14:17], v[150:153], v[218:221], v[14:17]
	v_mfma_f32_16x16x32_bf16 v[10:13], v[158:161], v[218:221], v[10:13]
	s_barrier
	s_sub_u32 m0, s62, 0x80
	s_nop 0
	global_load_lds_dwordx4 v249, s[28:29] offset:128
	s_sub_u32 m0, s63, 0x80
	s_nop 0
	global_load_lds_dwordx4 v248, s[28:29] offset:128
	s_waitcnt vmcnt(6)
	s_barrier
	v_mfma_f32_16x16x32_bf16 v[54:57], v[222:225], v[164:167], v[54:57]
	v_mfma_f32_16x16x32_bf16 v[50:53], v[230:233], v[164:167], v[50:53]
	v_mfma_f32_16x16x32_bf16 v[38:41], v[222:225], v[194:197], v[38:41]
	v_mfma_f32_16x16x32_bf16 v[34:37], v[230:233], v[194:197], v[34:37]
	v_mfma_f32_16x16x32_bf16 v[22:25], v[222:225], v[206:209], v[22:25]
	v_mfma_f32_16x16x32_bf16 v[18:21], v[230:233], v[206:209], v[18:21]
	v_mfma_f32_16x16x32_bf16 v[6:9], v[222:225], v[214:217], v[6:9]
	v_mfma_f32_16x16x32_bf16 v[2:5], v[230:233], v[214:217], v[2:5]
	v_mfma_f32_16x16x32_bf16 v[54:57], v[226:229], v[168:171], v[54:57]
	v_mfma_f32_16x16x32_bf16 v[50:53], v[234:237], v[168:171], v[50:53]
	v_mfma_f32_16x16x32_bf16 v[38:41], v[226:229], v[198:201], v[38:41]
	v_mfma_f32_16x16x32_bf16 v[34:37], v[234:237], v[198:201], v[34:37]
	v_mfma_f32_16x16x32_bf16 v[22:25], v[226:229], v[210:213], v[22:25]
	v_mfma_f32_16x16x32_bf16 v[18:21], v[234:237], v[210:213], v[18:21]
	v_mfma_f32_16x16x32_bf16 v[6:9], v[226:229], v[218:221], v[6:9]
	v_mfma_f32_16x16x32_bf16 v[2:5], v[234:237], v[218:221], v[2:5]
	s_add_u32 s26, s26, 0x100
	s_addc_u32 s27, s27, 0
	s_add_u32 s37, s37, 0x100
	s_addc_u32 s53, s53, 0
	s_cmp_ge_i32 s72, s49
	s_mov_b32 s2, s72
	s_barrier
	s_cbranch_scc0 .LBB0_1255
